# stick-breaking tile loop: next tile K/V LDS-DMA issued right after the current tile fragments are in registers (prefetch under the elementwise work)
# baseline (speedup 1.0000x reference)
.LBB0_291:
	s_waitcnt vmcnt(0)
	v_lshlrev_b32_e32 v32, 1, v164
	v_lshlrev_b32_e32 v33, 9, v165
	v_add3_u32 v32, s82, v32, v33
	v_cvt_pk_bf16_f32 v0, v0, s0
	ds_write_b16 v32, v0
	v_cvt_pk_bf16_f32 v0, v16, s0
	ds_write_b16 v32, v0 offset:64
	v_cvt_pk_bf16_f32 v0, v1, s0
	ds_write_b16 v32, v0 offset:128
	v_cvt_pk_bf16_f32 v0, v17, s0
	ds_write_b16 v32, v0 offset:192
	v_cvt_pk_bf16_f32 v0, v2, s0
	ds_write_b16 v32, v0 offset:256
	v_cvt_pk_bf16_f32 v0, v18, s0
	ds_write_b16 v32, v0 offset:320
	v_cvt_pk_bf16_f32 v0, v3, s0
	ds_write_b16 v32, v0 offset:384
	v_cvt_pk_bf16_f32 v0, v19, s0
	ds_write_b16 v32, v0 offset:448
	v_cvt_pk_bf16_f32 v0, v4, s0
	ds_write_b16 v32, v0 offset:1024
	v_cvt_pk_bf16_f32 v0, v20, s0
	ds_write_b16 v32, v0 offset:1088
	v_cvt_pk_bf16_f32 v0, v5, s0
	ds_write_b16 v32, v0 offset:1152
	v_cvt_pk_bf16_f32 v0, v21, s0
	ds_write_b16 v32, v0 offset:1216
	v_cvt_pk_bf16_f32 v0, v6, s0
	ds_write_b16 v32, v0 offset:1280
	v_cvt_pk_bf16_f32 v0, v22, s0
	ds_write_b16 v32, v0 offset:1344
	v_cvt_pk_bf16_f32 v0, v7, s0
	ds_write_b16 v32, v0 offset:1408
	v_cvt_pk_bf16_f32 v0, v23, s0
	ds_write_b16 v32, v0 offset:1472
	v_cvt_pk_bf16_f32 v0, v8, s0
	ds_write_b16 v32, v0 offset:2048
	v_cvt_pk_bf16_f32 v0, v24, s0
	ds_write_b16 v32, v0 offset:2112
	v_cvt_pk_bf16_f32 v0, v9, s0
	ds_write_b16 v32, v0 offset:2176
	v_cvt_pk_bf16_f32 v0, v25, s0
	ds_write_b16 v32, v0 offset:2240
	v_cvt_pk_bf16_f32 v0, v10, s0
	ds_write_b16 v32, v0 offset:2304
	v_cvt_pk_bf16_f32 v0, v26, s0
	ds_write_b16 v32, v0 offset:2368
	v_cvt_pk_bf16_f32 v0, v11, s0
	ds_write_b16 v32, v0 offset:2432
	v_cvt_pk_bf16_f32 v0, v27, s0
	ds_write_b16 v32, v0 offset:2496
	v_cvt_pk_bf16_f32 v0, v12, s0
	ds_write_b16 v32, v0 offset:3072
	v_cvt_pk_bf16_f32 v0, v28, s0
	ds_write_b16 v32, v0 offset:3136
	v_cvt_pk_bf16_f32 v0, v13, s0
	ds_write_b16 v32, v0 offset:3200
	v_cvt_pk_bf16_f32 v0, v29, s0
	ds_write_b16 v32, v0 offset:3264
	v_cvt_pk_bf16_f32 v0, v14, s0
	ds_write_b16 v32, v0 offset:3328
	v_cvt_pk_bf16_f32 v0, v30, s0
	ds_write_b16 v32, v0 offset:3392
	v_cvt_pk_bf16_f32 v0, v15, s0
	ds_write_b16 v32, v0 offset:3456
	v_cvt_pk_bf16_f32 v0, v31, s0
	v_lshlrev_b32_e32 v112, 4, v163
	ds_write_b16 v32, v0 offset:3520
	s_lshl_b64 s[0:1], s[10:11], 1
	v_readlane_b32 s2, v253, 27
	v_add_u32_e32 v12, s82, v112
	s_waitcnt lgkmcnt(0)
	v_readlane_b32 s3, v253, 28
	s_add_u32 s2, s2, s0
	v_lshl_add_u32 v0, v162, 7, v12
	v_or_b32_e32 v13, 8, v162
	s_addc_u32 s3, s3, s1
	s_lshl_b64 s[0:1], s[8:9], 1
	ds_read_b128 v[0:3], v0
	v_lshl_add_u32 v4, v13, 7, v12
	s_add_u32 s0, s2, s0
	ds_read_b128 v[4:7], v4
	s_addc_u32 s1, s3, s1
	v_lshl_add_u64 v[8:9], s[0:1], 0, v[112:113]
	v_mov_b32_e32 v115, v113
	v_lshl_add_u64 v[10:11], v[8:9], 0, v[114:115]
	v_lshlrev_b32_e32 v112, 11, v13
	s_waitcnt lgkmcnt(0)
	global_store_dwordx4 v[10:11], v[0:3], off
	v_or_b32_e32 v13, 24, v162
	s_add_i32 s33, s33, s58
	v_lshl_add_u64 v[0:1], v[8:9], 0, v[112:113]
	global_store_dwordx4 v[0:1], v[4:7], off
	s_cmpk_lt_i32 s33, 0x2000
	s_nop 0
	v_or_b32_e32 v4, 16, v162
	v_lshl_add_u32 v0, v4, 7, v12
	ds_read_b128 v[0:3], v0
	v_lshlrev_b32_e32 v112, 11, v4
	v_lshl_add_u32 v4, v13, 7, v12
	ds_read_b128 v[4:7], v4
	v_lshl_add_u64 v[10:11], v[8:9], 0, v[112:113]
	v_lshlrev_b32_e32 v112, 11, v13
	s_waitcnt lgkmcnt(0)
	global_store_dwordx4 v[10:11], v[0:3], off
	s_nop 1
	v_lshl_add_u64 v[0:1], v[8:9], 0, v[112:113]
	global_store_dwordx4 v[0:1], v[4:7], off
	s_waitcnt lgkmcnt(0)
	s_cbranch_scc0 .LBB0_309

.LBB0_294:
	s_cmp_lg_u32 s80, 0
	s_cbranch_scc1 .Lsb_skipdma
	s_sub_i32 s86, s2, 56
	s_lshl_b64 s[94:95], s[86:87], 11
	v_lshl_add_u64 v[32:33], v[116:117], 0, s[94:95]
	s_mov_b32 s3, m0
	s_mov_b32 m0, s82
	s_nop 0
	global_load_lds_dwordx4 v[32:33], off
	s_mov_b32 m0, s3
	s_sub_i32 s86, s2, 48
	s_lshl_b64 s[96:97], s[86:87], 11
	s_add_i32 s3, s82, 0x400
	s_sub_i32 s86, s2, 40
	v_lshl_add_u64 v[32:33], v[116:117], 0, s[96:97]
	s_mov_b32 s81, m0
	s_mov_b32 m0, s3
	s_nop 0
	global_load_lds_dwordx4 v[32:33], off
	s_mov_b32 m0, s81
	s_lshl_b64 s[96:97], s[86:87], 11
	s_add_i32 s3, s82, 0x800
	s_sub_i32 s86, s2, 32
	v_lshl_add_u64 v[32:33], v[116:117], 0, s[96:97]
	s_mov_b32 s81, m0
	s_mov_b32 m0, s3
	s_nop 0
	global_load_lds_dwordx4 v[32:33], off
	s_mov_b32 m0, s81
	s_lshl_b64 vcc, s[86:87], 11
	s_add_i32 s3, s82, 0xc00
	s_sub_i32 s86, s2, 24
	v_lshl_add_u64 v[32:33], v[116:117], 0, vcc
	s_mov_b32 s81, m0
	s_mov_b32 m0, s3
	s_nop 0
	global_load_lds_dwordx4 v[32:33], off
	s_mov_b32 m0, s81
	s_lshl_b64 vcc, s[86:87], 11
	s_add_i32 s3, s82, 0x1000
	s_add_i32 s86, s2, -16
	v_lshl_add_u64 v[32:33], v[116:117], 0, vcc
	s_mov_b32 s81, m0
	s_mov_b32 m0, s3
	s_nop 0
	global_load_lds_dwordx4 v[32:33], off
	s_mov_b32 m0, s81
	s_lshl_b64 s[88:89], s[86:87], 11
	s_add_i32 s3, s82, 0x1400
	s_add_i32 s86, s2, -8
	v_lshl_add_u64 v[32:33], v[116:117], 0, s[88:89]
	s_mov_b32 s81, m0
	s_mov_b32 m0, s3
	s_nop 0
	global_load_lds_dwordx4 v[32:33], off
	s_mov_b32 m0, s81
	s_lshl_b64 s[88:89], s[86:87], 11
	s_add_i32 s3, s82, 0x1800
	v_lshl_add_u64 v[32:33], v[116:117], 0, s[88:89]
	s_mov_b32 s81, m0
	s_mov_b32 m0, s3
	s_nop 0
	global_load_lds_dwordx4 v[32:33], off
	s_mov_b32 m0, s81
	s_mov_b32 s3, s87
	s_lshl_b64 s[90:91], s[2:3], 11
	v_lshl_add_u64 v[32:33], v[116:117], 0, s[90:91]
	s_add_i32 s3, s82, 0x1c00
	s_mov_b32 s81, m0
	s_mov_b32 m0, s3
	s_nop 0
	global_load_lds_dwordx4 v[32:33], off
	s_mov_b32 m0, s81
	v_lshl_add_u64 v[32:33], v[118:119], 0, s[94:95]
	s_mov_b32 s3, m0
	s_mov_b32 m0, s83
	s_nop 0
	global_load_lds_dwordx4 v[32:33], off
	s_mov_b32 m0, s3
	v_lshl_add_u64 v[34:35], v[118:119], 0, s[96:97]
	s_add_i32 s3, s82, 0x2400
	s_mov_b32 s81, m0
	s_mov_b32 m0, s3
	s_nop 0
	global_load_lds_dwordx4 v[34:35], off
	s_mov_b32 m0, s81
	v_lshl_add_u64 v[36:37], v[118:119], 0, vcc
	s_add_i32 s3, s82, 0x2800
	s_mov_b32 s81, m0
	s_mov_b32 m0, s3
	s_nop 0
	global_load_lds_dwordx4 v[36:37], off
	s_mov_b32 m0, s81
	v_lshl_add_u64 v[38:39], v[118:119], 0, s[88:89]
	s_add_i32 s3, s82, 0x2c00
	s_mov_b32 s81, m0
	s_mov_b32 m0, s3
	s_nop 0
	global_load_lds_dwordx4 v[38:39], off
	s_mov_b32 m0, s81
	v_lshl_add_u64 v[32:33], v[32:33], 0, 64
	s_add_i32 s3, s82, 0x3000
	s_mov_b32 s81, m0
	s_mov_b32 m0, s3
	s_nop 0
	global_load_lds_dwordx4 v[32:33], off
	s_mov_b32 m0, s81
	v_lshl_add_u64 v[32:33], v[34:35], 0, 64
	s_add_i32 s3, s82, 0x3400
	s_mov_b32 s81, m0
	s_mov_b32 m0, s3
	s_nop 0
	global_load_lds_dwordx4 v[32:33], off
	s_mov_b32 m0, s81
	v_lshl_add_u64 v[32:33], v[36:37], 0, 64
	s_add_i32 s3, s82, 0x3800
	s_mov_b32 s81, m0
	s_mov_b32 m0, s3
	s_nop 0
	global_load_lds_dwordx4 v[32:33], off
	s_mov_b32 m0, s81
	v_lshl_add_u64 v[32:33], v[38:39], 0, 64
	s_add_i32 s3, s82, 0x3c00
	s_mov_b32 s81, m0
	s_mov_b32 m0, s3
	s_nop 0
	global_load_lds_dwordx4 v[32:33], off
	s_mov_b32 m0, s81
.Lsb_skipdma:
	s_waitcnt vmcnt(0)
	ds_read_b128 v[32:35], v115
	ds_read_b128 v[48:51], v115 offset:4096
	ds_read_b128 v[80:83], v166
	ds_read_b128 v[84:87], v166 offset:4096
	ds_read_b128 v[88:91], v167
	ds_read_b128 v[92:95], v167 offset:4096
	ds_read_b128 v[96:99], v168
	ds_read_b128 v[100:103], v168 offset:4096
	s_waitcnt vmcnt(0) lgkmcnt(0)
	v_mfma_f32_32x32x16_bf16 v[32:47], v[32:35], v[76:79], 0
	v_mfma_f32_32x32x16_bf16 v[48:63], v[48:51], v[76:79], 0
	v_mfma_f32_32x32x16_bf16 v[32:47], v[80:83], v[72:75], v[32:47]
	v_mfma_f32_32x32x16_bf16 v[48:63], v[84:87], v[72:75], v[48:63]
	v_mfma_f32_32x32x16_bf16 v[32:47], v[88:91], v[68:71], v[32:47]
	v_mfma_f32_32x32x16_bf16 v[48:63], v[92:95], v[68:71], v[48:63]
	v_mfma_f32_32x32x16_bf16 v[32:47], v[96:99], v[64:67], v[32:47]
	v_mfma_f32_32x32x16_bf16 v[48:63], v[100:103], v[64:67], v[48:63]
	ds_read_b64_tr_b16 v[88:89], v169 offset:8192
	ds_read_b64_tr_b16 v[90:91], v169 offset:8704
	ds_read_b64_tr_b16 v[84:85], v169 offset:12288
	ds_read_b64_tr_b16 v[86:87], v169 offset:12800
	ds_read_b64_tr_b16 v[92:93], v169 offset:9216
	ds_read_b64_tr_b16 v[94:95], v169 offset:9728
	ds_read_b64_tr_b16 v[108:109], v169 offset:13312
	ds_read_b64_tr_b16 v[110:111], v169 offset:13824
	ds_read_b64_tr_b16 v[104:105], v169 offset:10240
	ds_read_b64_tr_b16 v[106:107], v169 offset:10752
	ds_read_b64_tr_b16 v[96:97], v169 offset:14336
	ds_read_b64_tr_b16 v[98:99], v169 offset:14848
	ds_read_b64_tr_b16 v[100:101], v169 offset:11264
	ds_read_b64_tr_b16 v[102:103], v169 offset:11776
	ds_read_b64_tr_b16 v[80:81], v169 offset:15360
	ds_read_b64_tr_b16 v[82:83], v169 offset:15872
	s_cmp_lt_u32 s80, s85
	s_cbranch_scc0 .Lsb_nopf
	s_waitcnt lgkmcnt(0)
	s_mov_b32 s32, m0
	s_sub_i32 s100, s2, 0x78
	s_lshl_b32 s100, s100, 11
	s_mov_b32 s101, 0
	s_mov_b32 s98, 0x4000
	s_mov_b32 s99, 0
	v_lshl_add_u64 v[202:203], v[116:117], 0, s[100:101]
	s_mov_b32 m0, s82
	s_nop 0
	global_load_lds_dwordx4 v[202:203], off
	v_lshl_add_u64 v[202:203], v[202:203], 0, s[98:99]
	s_add_i32 m0, s82, 0x400
	s_nop 0
	global_load_lds_dwordx4 v[202:203], off
	v_lshl_add_u64 v[202:203], v[202:203], 0, s[98:99]
	s_add_i32 m0, s82, 0x800
	s_nop 0
	global_load_lds_dwordx4 v[202:203], off
	v_lshl_add_u64 v[202:203], v[202:203], 0, s[98:99]
	s_add_i32 m0, s82, 0xc00
	s_nop 0
	global_load_lds_dwordx4 v[202:203], off
	v_lshl_add_u64 v[202:203], v[202:203], 0, s[98:99]
	s_add_i32 m0, s82, 0x1000
	s_nop 0
	global_load_lds_dwordx4 v[202:203], off
	v_lshl_add_u64 v[202:203], v[202:203], 0, s[98:99]
	s_add_i32 m0, s82, 0x1400
	s_nop 0
	global_load_lds_dwordx4 v[202:203], off
	v_lshl_add_u64 v[202:203], v[202:203], 0, s[98:99]
	s_add_i32 m0, s82, 0x1800
	s_nop 0
	global_load_lds_dwordx4 v[202:203], off
	v_lshl_add_u64 v[202:203], v[202:203], 0, s[98:99]
	s_add_i32 m0, s82, 0x1c00
	s_nop 0
	global_load_lds_dwordx4 v[202:203], off
	s_mov_b32 s98, 0x8000
	v_lshl_add_u64 v[204:205], v[118:119], 0, s[100:101]
	s_add_i32 m0, s82, 0x2000
	s_nop 0
	global_load_lds_dwordx4 v[204:205], off
	v_lshl_add_u64 v[204:205], v[204:205], 0, s[98:99]
	s_add_i32 m0, s82, 0x2400
	s_nop 0
	global_load_lds_dwordx4 v[204:205], off
	v_lshl_add_u64 v[204:205], v[204:205], 0, s[98:99]
	s_add_i32 m0, s82, 0x2800
	s_nop 0
	global_load_lds_dwordx4 v[204:205], off
	v_lshl_add_u64 v[204:205], v[204:205], 0, s[98:99]
	s_add_i32 m0, s82, 0x2c00
	s_nop 0
	global_load_lds_dwordx4 v[204:205], off
	v_lshl_add_u64 v[204:205], v[118:119], 0, s[100:101]
	v_lshl_add_u64 v[204:205], v[204:205], 0, 64
	s_add_i32 m0, s82, 0x3000
	s_nop 0
	global_load_lds_dwordx4 v[204:205], off
	v_lshl_add_u64 v[204:205], v[204:205], 0, s[98:99]
	s_add_i32 m0, s82, 0x3400
	s_nop 0
	global_load_lds_dwordx4 v[204:205], off
	v_lshl_add_u64 v[204:205], v[204:205], 0, s[98:99]
	s_add_i32 m0, s82, 0x3800
	s_nop 0
	global_load_lds_dwordx4 v[204:205], off
	v_lshl_add_u64 v[204:205], v[204:205], 0, s[98:99]
	s_add_i32 m0, s82, 0x3c00
	s_nop 0
	global_load_lds_dwordx4 v[204:205], off
	s_mov_b32 m0, s32
.Lsb_nopf:
	s_cmp_lg_u32 s80, 0
	s_cbranch_scc0 .LBB0_297
	v_exp_f32_e64 v120, -|v51|
	v_exp_f32_e64 v112, -|v48|
	v_and_b32_e32 v125, 0x7fffffff, v55
	v_and_b32_e32 v124, 0x7fffffff, v54
	v_add_f32_e32 v120, 1.0, v120
	v_add_f32_e32 v112, 1.0, v112
	v_log_f32_e32 v122, v120
	v_log_f32_e32 v146, v112
	v_add_f32_e64 v120, v51, |v51|
	v_add_f32_e64 v112, v48, |v48|
	v_fmac_f32_e32 v122, 0.5, v120
	v_exp_f32_e64 v120, -|v55|
	v_fmac_f32_e32 v146, 0.5, v112
	v_exp_f32_e64 v112, -|v54|
	v_pk_add_f32 v[124:125], v[54:55], v[124:125]
	v_add_f32_e32 v120, 1.0, v120
	v_log_f32_e32 v127, v120
	v_add_f32_e32 v112, 1.0, v112
	v_exp_f32_e64 v120, -|v59|
	v_log_f32_e32 v126, v112
	v_exp_f32_e64 v112, -|v56|
	v_add_f32_e64 v123, v56, |v56|
	v_add_f32_e32 v120, 1.0, v120
	v_pk_fma_f32 v[126:127], v[124:125], 0.5, v[126:127] op_sel_hi:[1,0,1]
	v_log_f32_e32 v124, v120
	v_exp_f32_e64 v120, -|v62|
	v_exp_f32_e64 v125, -|v63|
	v_add_f32_e32 v112, 1.0, v112
	v_log_f32_e32 v112, v112
	v_add_f32_e32 v120, 1.0, v120
	v_log_f32_e32 v128, v120
	v_add_f32_e32 v120, 1.0, v125
	v_log_f32_e32 v129, v120
	v_exp_f32_e64 v120, -|v57|
	v_fmac_f32_e32 v112, 0.5, v123
	v_add_f32_e64 v123, v59, |v59|
	v_fmac_f32_e32 v124, 0.5, v123
	v_add_f32_e32 v120, 1.0, v120
	v_log_f32_e32 v138, v120
	v_exp_f32_e64 v120, -|v58|
	v_exp_f32_e64 v123, -|v60|
	v_exp_f32_e64 v125, -|v61|
	v_and_b32_e32 v131, 0x7fffffff, v63
	v_add_f32_e32 v120, 1.0, v120
	v_log_f32_e32 v144, v120
	v_add_f32_e32 v120, 1.0, v123
	v_log_f32_e32 v139, v120
	v_add_f32_e32 v120, 1.0, v125
	v_and_b32_e32 v130, 0x7fffffff, v62
	v_log_f32_e32 v145, v120
	v_pk_add_f32 v[130:131], v[62:63], v[130:131]
	v_and_b32_e32 v135, 0x7fffffff, v60
	v_mov_b32_e32 v136, v57
	v_mov_b32_e32 v137, v60
	v_and_b32_e32 v134, 0x7fffffff, v57
	v_pk_fma_f32 v[128:129], v[130:131], 0.5, v[128:129] op_sel_hi:[1,0,1]
	v_and_b32_e32 v141, 0x7fffffff, v61
	v_mov_b32_e32 v142, v58
	v_mov_b32_e32 v143, v61
	v_and_b32_e32 v140, 0x7fffffff, v58
	v_pk_add_f32 v[134:135], v[136:137], v[134:135]
	v_pk_add_f32 v[130:131], v[128:129], v[128:129] op_sel:[0,1] op_sel_hi:[1,0]
	v_pk_fma_f32 v[136:137], v[134:135], 0.5, v[138:139] op_sel_hi:[1,0,1]
	v_pk_add_f32 v[134:135], v[142:143], v[140:141]
	v_mov_b32_e32 v125, v130
	v_pk_fma_f32 v[134:135], v[134:135], 0.5, v[144:145] op_sel_hi:[1,0,1]
	v_exp_f32_e64 v120, -|v52|
	v_pk_add_f32 v[134:135], v[134:135], v[124:125]
	v_exp_f32_e64 v123, -|v53|
	v_pk_add_f32 v[136:137], v[136:137], v[134:135]
	v_and_b32_e32 v143, 0x7fffffff, v52
	v_pk_add_f32 v[138:139], v[112:113], v[136:137]
	v_exp_f32_e64 v112, -|v49|
	v_mov_b32_e32 v144, v49
	v_mov_b32_e32 v145, v52
	v_and_b32_e32 v142, 0x7fffffff, v49
	v_add_f32_e32 v112, 1.0, v112
	v_log_f32_e32 v148, v112
	v_exp_f32_e64 v112, -|v50|
	v_and_b32_e32 v151, 0x7fffffff, v53
	v_mov_b32_e32 v152, v50
	v_mov_b32_e32 v153, v53
	v_add_f32_e32 v112, 1.0, v112
	v_log_f32_e32 v154, v112
	v_add_f32_e32 v112, 1.0, v120
	v_log_f32_e32 v149, v112
	v_add_f32_e32 v112, 1.0, v123
	v_log_f32_e32 v155, v112
	v_and_b32_e32 v150, 0x7fffffff, v50
	v_pk_add_f32 v[142:143], v[144:145], v[142:143]
	v_pk_add_f32 v[132:133], v[126:127], v[126:127] op_sel:[0,1] op_sel_hi:[1,0]
	v_pk_fma_f32 v[144:145], v[142:143], 0.5, v[148:149] op_sel_hi:[1,0,1]
	v_pk_add_f32 v[142:143], v[152:153], v[150:151]
	v_mov_b32_e32 v123, v132
	v_pk_fma_f32 v[142:143], v[142:143], 0.5, v[154:155] op_sel_hi:[1,0,1]
	v_pk_add_f32 v[140:141], v[138:139], v[138:139] op_sel:[0,1] op_sel_hi:[1,0]
	v_pk_add_f32 v[142:143], v[142:143], v[122:123]
	v_mov_b32_e32 v147, v140
	v_pk_add_f32 v[144:145], v[144:145], v[142:143]
	v_mov_b32_e32 v125, v140
	v_pk_add_f32 v[146:147], v[146:147], v[144:145]
	v_mov_b32_e32 v126, v140
	v_add_f32_e32 v112, v146, v147
	v_mov_b32_e32 v120, v112
	v_mov_b32_e32 v123, v147
	s_nop 1
	v_permlane32_swap_b32_e32 v120, v123
	v_cndmask_b32_e64 v123, v120, v123, s[74:75]
	v_add_f32_e32 v112, v112, v123
	v_mov_b32_e32 v120, v112
	v_mov_b32_e32 v133, v112
	s_nop 1
	v_permlane32_swap_b32_e32 v120, v133
	v_cndmask_b32_e64 v120, v120, v133, s[74:75]
	v_cndmask_b32_e64 v112, v120, v112, s[74:75]
	v_add_f32_e32 v120, v121, v112
	v_mov_b32_e32 v131, v147
	v_mov_b32_e32 v141, v139
	v_mov_b32_e32 v128, v139
	v_mov_b32_e32 v170, 0
	v_cmp_lt_f32_e32 vcc, s84, v120
	v_permlane32_swap_b32_e32 v131, v125
	v_permlane32_swap_b32_e32 v126, v141
	s_cmp_eq_u64 vcc, exec
	v_permlane32_swap_b32_e32 v128, v170
	s_cbranch_scc1 .LBB0_298
	v_exp_f32_e64 v112, -|v32|
	v_add_f32_e64 v133, v40, |v40|
	v_and_b32_e32 v153, 0x7fffffff, v39
	v_and_b32_e32 v152, 0x7fffffff, v38
	v_add_f32_e32 v112, 1.0, v112
	v_log_f32_e32 v150, v112
	v_add_f32_e64 v112, v32, |v32|
	v_pk_add_f32 v[152:153], v[38:39], v[152:153]
	v_and_b32_e32 v157, 0x7fffffff, v47
	v_fmac_f32_e32 v150, 0.5, v112
	v_exp_f32_e64 v112, -|v35|
	v_and_b32_e32 v156, 0x7fffffff, v46
	v_pk_add_f32 v[156:157], v[46:47], v[156:157]
	v_and_b32_e32 v173, 0x7fffffff, v44
	v_add_f32_e32 v112, 1.0, v112
	v_log_f32_e32 v148, v112
	v_add_f32_e64 v112, v35, |v35|
	v_mov_b32_e32 v174, v41
	v_mov_b32_e32 v175, v44
	v_fmac_f32_e32 v148, 0.5, v112
	v_exp_f32_e64 v112, -|v38|
	v_and_b32_e32 v172, 0x7fffffff, v41
	v_and_b32_e32 v179, 0x7fffffff, v45
	v_mov_b32_e32 v180, v42
	v_add_f32_e32 v112, 1.0, v112
	v_log_f32_e32 v154, v112
	v_exp_f32_e64 v112, -|v39|
	v_mov_b32_e32 v181, v45
	v_and_b32_e32 v178, 0x7fffffff, v42
	v_pk_add_f32 v[172:173], v[174:175], v[172:173]
	v_add_f32_e32 v112, 1.0, v112
	v_log_f32_e32 v155, v112
	v_exp_f32_e64 v112, -|v40|
	v_pk_add_f32 v[174:175], v[180:181], v[178:179]
	v_and_b32_e32 v181, 0x7fffffff, v36
	v_pk_fma_f32 v[152:153], v[152:153], 0.5, v[154:155] op_sel_hi:[1,0,1]
	v_add_f32_e32 v112, 1.0, v112
	v_log_f32_e32 v112, v112
	v_and_b32_e32 v180, 0x7fffffff, v33
	v_and_b32_e32 v189, 0x7fffffff, v37
	v_mov_b32_e32 v192, v34
	v_fmac_f32_e32 v112, 0.5, v133
	v_exp_f32_e64 v133, -|v43|
	v_mov_b32_e32 v193, v37
	v_and_b32_e32 v188, 0x7fffffff, v34
	v_pk_add_f32 v[160:161], v[152:153], v[152:153] op_sel:[0,1] op_sel_hi:[1,0]
	v_add_f32_e32 v133, 1.0, v133
	v_log_f32_e32 v154, v133
	v_add_f32_e64 v133, v43, |v43|
	v_mov_b32_e32 v149, v160
	s_mov_b64 s[94:95], 0
	v_fmac_f32_e32 v154, 0.5, v133
	v_exp_f32_e64 v133, -|v46|
	s_nop 0
	v_add_f32_e32 v133, 1.0, v133
	v_log_f32_e32 v158, v133
	v_exp_f32_e64 v133, -|v47|
	s_nop 0
	v_add_f32_e32 v133, 1.0, v133
	v_log_f32_e32 v159, v133
	v_exp_f32_e64 v133, -|v41|
	v_pk_fma_f32 v[156:157], v[156:157], 0.5, v[158:159] op_sel_hi:[1,0,1]
	v_add_f32_e32 v133, 1.0, v133
	v_log_f32_e32 v176, v133
	v_exp_f32_e64 v133, -|v42|
	v_pk_add_f32 v[158:159], v[156:157], v[156:157] op_sel:[0,1] op_sel_hi:[1,0]
	v_add_f32_e32 v133, 1.0, v133
	v_log_f32_e32 v182, v133
	v_exp_f32_e64 v133, -|v44|
	v_mov_b32_e32 v155, v158
	v_add_f32_e32 v133, 1.0, v133
	v_log_f32_e32 v177, v133
	v_exp_f32_e64 v133, -|v45|
	v_pk_fma_f32 v[172:173], v[172:173], 0.5, v[176:177] op_sel_hi:[1,0,1]
	v_add_f32_e32 v133, 1.0, v133
	v_log_f32_e32 v183, v133
	s_nop 0
	v_pk_fma_f32 v[174:175], v[174:175], 0.5, v[182:183] op_sel_hi:[1,0,1]
	s_nop 0
	v_pk_add_f32 v[174:175], v[174:175], v[154:155]
	v_mov_b32_e32 v182, v33
	v_pk_add_f32 v[172:173], v[172:173], v[174:175]
	v_mov_b32_e32 v183, v36
	v_pk_add_f32 v[176:177], v[112:113], v[172:173]
	v_exp_f32_e64 v112, -|v33|
	v_pk_add_f32 v[180:181], v[182:183], v[180:181]
	v_pk_add_f32 v[182:183], v[192:193], v[188:189]
	v_pk_add_f32 v[178:179], v[176:177], v[176:177] op_sel:[0,1] op_sel_hi:[1,0]
	v_add_f32_e32 v112, 1.0, v112
	v_log_f32_e32 v186, v112
	v_exp_f32_e64 v112, -|v34|
	v_mov_b32_e32 v151, v178
	v_add_f32_e32 v152, v177, v120
	v_add_f32_e32 v155, 0, v120
	v_add_f32_e32 v112, 1.0, v112
	v_log_f32_e32 v194, v112
	v_exp_f32_e64 v112, -|v36|
	s_nop 0
	v_add_f32_e32 v112, 1.0, v112
	v_log_f32_e32 v187, v112
	v_exp_f32_e64 v112, -|v37|
	v_pk_fma_f32 v[180:181], v[180:181], 0.5, v[186:187] op_sel_hi:[1,0,1]
	v_add_f32_e32 v112, 1.0, v112
	v_log_f32_e32 v195, v112
	s_nop 0
	v_pk_fma_f32 v[182:183], v[182:183], 0.5, v[194:195] op_sel_hi:[1,0,1]
	s_nop 0
	v_pk_add_f32 v[186:187], v[182:183], v[148:149]
	s_nop 0
	v_pk_add_f32 v[188:189], v[180:181], v[186:187]
	s_nop 0
	v_pk_add_f32 v[150:151], v[150:151], v[188:189]
	s_nop 0
	v_add_f32_e32 v112, v150, v151
	v_mov_b32_e32 v133, v112
	v_mov_b32_e32 v149, v151
	s_nop 1
	v_permlane32_swap_b32_e32 v133, v149
	v_cndmask_b32_e64 v133, v133, v149, s[74:75]
	v_add_f32_e32 v149, v151, v120
	v_add_f32_e32 v149, v149, v133
	v_add_f32_e32 v112, v112, v133
	v_mov_b32_e32 v133, v178
	s_nop 1
	v_permlane32_swap_b32_e32 v151, v133
	v_cndmask_b32_e64 v133, v151, v133, s[74:75]
	v_add_f32_e32 v151, v178, v120
	v_add_f32_e32 v151, v151, v133
	v_mov_b32_e32 v133, v177
	s_nop 1
	v_permlane32_swap_b32_e32 v178, v133
	v_cndmask_b32_e64 v133, v178, v133, s[74:75]
	v_add_f32_e32 v152, v152, v133
	v_mov_b32_e32 v133, v113
	s_nop 1
	v_permlane32_swap_b32_e32 v177, v133
	v_cndmask_b32_e64 v133, v177, v133, s[74:75]
	v_add_f32_e32 v155, v155, v133
	v_mov_b32_e32 v133, v112
	v_mov_b32_e32 v156, v112
	s_nop 1
	v_permlane32_swap_b32_e32 v133, v156
	v_cndmask_b32_e64 v133, v133, v156, s[74:75]
	v_cndmask_b32_e64 v112, v133, v112, s[74:75]
	v_add_f32_e32 v120, v120, v112
	v_add_f32_e32 v112, v150, v149
	v_sub_f32_e32 v112, v32, v112
	v_exp_f32_e32 v133, v112
	v_add_f32_e32 v112, v188, v149
	v_sub_f32_e32 v112, v33, v112
	v_exp_f32_e32 v179, v112
	v_add_f32_e32 v112, v186, v149
	v_sub_f32_e32 v112, v34, v112
	v_exp_f32_e32 v181, v112
	v_add_f32_e32 v112, v148, v149
	v_add_f32_e32 v148, v172, v152
	v_sub_f32_e32 v148, v41, v148
	v_exp_f32_e32 v177, v148
	v_add_f32_e32 v148, v174, v152
	v_sub_f32_e32 v112, v35, v112
	v_sub_f32_e32 v148, v42, v148
	v_exp_f32_e32 v183, v112
	v_add_f32_e32 v112, v189, v151
	v_exp_f32_e32 v178, v148
	v_add_f32_e32 v148, v154, v152
	v_sub_f32_e32 v112, v36, v112
	v_sub_f32_e32 v148, v43, v148
	v_exp_f32_e32 v186, v112
	v_add_f32_e32 v112, v187, v151
	v_exp_f32_e32 v180, v148
	v_add_f32_e32 v148, v173, v155
	v_sub_f32_e32 v112, v37, v112
	v_sub_f32_e32 v148, v44, v148
	v_exp_f32_e32 v188, v112
	v_add_f32_e32 v112, v160, v151
	v_exp_f32_e32 v182, v148
	v_add_f32_e32 v148, v175, v155
	v_sub_f32_e32 v112, v38, v112
	v_sub_f32_e32 v148, v45, v148
	v_exp_f32_e32 v191, v112
	v_add_f32_e32 v112, v153, v151
	v_exp_f32_e32 v185, v148
	v_add_f32_e32 v148, v158, v155
	v_sub_f32_e32 v112, v39, v112
	v_sub_f32_e32 v148, v46, v148
	v_exp_f32_e32 v192, v112
	v_add_f32_e32 v112, v176, v152
	v_exp_f32_e32 v187, v148
	v_add_f32_e32 v148, v157, v155
	v_sub_f32_e32 v112, v40, v112
	v_sub_f32_e32 v148, v47, v148
	v_exp_f32_e32 v112, v112
	v_exp_f32_e32 v189, v148
	s_branch .LBB0_299
